# MLA QK phase: K-fragment waits merged pairwise (on top of v10)
# baseline (speedup 1.0000x reference)
; __device__ __forceinline__ int crow(int r, int hi) { return (r & 3) + 8 * (r >> 2) + 4 * hi; }
; #define MFMA32(a, b, c) __builtin_amdgcn_mfma_f32_32x32x16_bf16((a), (b), (c), 0, 0, 0)
; __device__ __forceinline__ void mla_attn_phase(const Ctx&, unsigned char* ws) { const Ctx c = mk_ctx();
;     ...
;             if (j <= my_last) {
;                 f32x16 p0 = f32x16{}, p1 = f32x16{};
; #pragma unroll
;                 for (int s = 0; s < 6; ++s) { const bf16x8 a0 = *(const bf16x8*)(Kb + r * KLD + 16 * s + 8 * hi), a1 = *(const bf16x8*)(Kb + (r + 32) * KLD + 16 * s + 8 * hi); p0 = MFMA32(a0, qr[s], p0); p1 = MFMA32(a1, qr[s], p1); }
;                 if (64 * j + 63 > qw0) { const int qq = qw0 + r - 64 * j;
; #pragma unroll
;                     for (int i = 0; i < 16; ++i) { const int kr_ = crow(i, hi); if (kr_ > qq) p0[i] = -INFINITY; if (kr_ + 32 > qq) p1[i] = -INFINITY; } }
.LBB0_751:
	s_cmp_gt_i32 s41, s36
	s_cbranch_scc1 .LBB0_755
	v_add3_u32 v242, s43, v155, v150
	ds_read_b128 v[190:193], v242
	ds_read_b128 v[214:217], v242 offset:6656
	ds_read_b128 v[218:221], v242 offset:32
	ds_read_b128 v[222:225], v242 offset:6688
	ds_read_b128 v[226:229], v242 offset:64
	ds_read_b128 v[230:233], v242 offset:6720
	ds_read_b128 v[234:237], v242 offset:96
	ds_read_b128 v[238:241], v242 offset:6752
	s_cmp_le_i32 s37, s34
	v_mfma_f32_32x32x8_bf16 v[50:65], v[246:247], v[252:253], 0
	v_add3_u32 v243, s39, v108, v185
	v_mfma_f32_32x32x8_bf16 v[34:49], v[246:247], v[252:253], 0
	v_add_u32_e32 v243, 0x6800, v243
	s_waitcnt lgkmcnt(6)
	v_mfma_f32_32x32x16_bf16 v[50:65], v[190:193], v[66:69], v[50:65]
	v_add_u32_e32 v244, 0x1000, v243
	v_mfma_f32_32x32x16_bf16 v[34:49], v[214:217], v[66:69], v[34:49]
	ds_read_b128 v[190:193], v242 offset:128
	ds_read_b128 v[214:217], v242 offset:6784
	s_waitcnt lgkmcnt(6)
	v_mfma_f32_32x32x16_bf16 v[50:65], v[218:221], v[70:73], v[50:65]
	v_mfma_f32_32x32x16_bf16 v[34:49], v[222:225], v[70:73], v[34:49]
	ds_read_b128 v[218:221], v242 offset:160
	ds_read_b128 v[222:225], v242 offset:6816
	s_waitcnt lgkmcnt(6)
	v_mfma_f32_32x32x16_bf16 v[50:65], v[226:229], v[74:77], v[50:65]
	v_mfma_f32_32x32x16_bf16 v[34:49], v[230:233], v[74:77], v[34:49]
	s_waitcnt lgkmcnt(4)
	v_mfma_f32_32x32x16_bf16 v[50:65], v[234:237], v[78:81], v[50:65]
	v_mfma_f32_32x32x16_bf16 v[34:49], v[238:241], v[78:81], v[34:49]
	s_waitcnt lgkmcnt(2)
	v_mfma_f32_32x32x16_bf16 v[50:65], v[190:193], v[82:85], v[50:65]
	v_mfma_f32_32x32x16_bf16 v[34:49], v[214:217], v[82:85], v[34:49]
	s_waitcnt lgkmcnt(0)
	v_mfma_f32_32x32x16_bf16 v[50:65], v[218:221], v[86:89], v[50:65]
	v_mfma_f32_32x32x16_bf16 v[34:49], v[222:225], v[86:89], v[34:49]
	ds_read2_b64 v[226:229], v243 offset0:0 offset1:2
	ds_read2_b64 v[230:233], v243 offset0:4 offset1:6
	ds_read2_b64 v[234:237], v243 offset0:8 offset1:10
	ds_read2_b64 v[238:241], v243 offset0:12 offset1:14
	ds_read2_b64 v[190:193], v244 offset0:32 offset1:34
	ds_read2_b64 v[214:217], v244 offset0:36 offset1:38
	ds_read2_b64 v[218:221], v244 offset0:40 offset1:42
	ds_read2_b64 v[222:225], v244 offset0:44 offset1:46
	s_nop 3
	s_cbranch_scc1 .Lmla_nomask
	v_cmp_le_i32_e32 vcc, v121, v187
	s_nop 1
	v_cndmask_b32_e32 v34, v208, v34, vcc
	v_cmp_lt_i32_e32 vcc, v118, v187
	s_nop 1
	v_cndmask_b32_e32 v51, v208, v51, vcc
	v_cmp_le_i32_e32 vcc, v118, v187
	s_nop 1
	v_cndmask_b32_e32 v50, v208, v50, vcc
	v_cmp_le_i32_e32 vcc, v156, v187
	s_nop 1
	v_cndmask_b32_e32 v35, v208, v35, vcc
	v_cmp_le_i32_e32 vcc, v157, v187
	s_nop 1
	v_cndmask_b32_e32 v52, v208, v52, vcc
	v_cmp_le_i32_e32 vcc, v158, v187
	s_nop 1
	v_cndmask_b32_e32 v36, v208, v36, vcc
	v_cmp_le_i32_e32 vcc, v159, v187
	s_nop 1
	v_cndmask_b32_e32 v53, v208, v53, vcc
	v_cmp_le_i32_e32 vcc, v160, v187
	s_nop 1
	v_cndmask_b32_e32 v37, v208, v37, vcc
	v_cmp_le_i32_e32 vcc, v161, v187
	s_nop 1
	v_cndmask_b32_e32 v54, v208, v54, vcc
	v_cmp_le_i32_e32 vcc, v162, v187
	s_nop 1
	v_cndmask_b32_e32 v38, v208, v38, vcc
	v_cmp_le_i32_e32 vcc, v163, v187
	s_nop 1
	v_cndmask_b32_e32 v55, v208, v55, vcc
	v_cmp_le_i32_e32 vcc, v164, v187
	s_nop 1
	v_cndmask_b32_e32 v39, v208, v39, vcc
	v_cmp_le_i32_e32 vcc, v165, v187
	s_nop 1
	v_cndmask_b32_e32 v56, v208, v56, vcc
	v_cmp_le_i32_e32 vcc, v166, v187
	s_nop 1
	v_cndmask_b32_e32 v40, v208, v40, vcc
	v_cmp_le_i32_e32 vcc, v167, v187
	s_nop 1
	v_cndmask_b32_e32 v57, v208, v57, vcc
	v_cmp_le_i32_e32 vcc, v168, v187
	s_nop 1
	v_cndmask_b32_e32 v41, v208, v41, vcc
	v_cmp_le_i32_e32 vcc, v169, v187
	s_nop 1
	v_cndmask_b32_e32 v58, v208, v58, vcc
	v_cmp_le_i32_e32 vcc, v170, v187
	s_nop 1
	v_cndmask_b32_e32 v42, v208, v42, vcc
	v_cmp_le_i32_e32 vcc, v171, v187
	s_nop 1
	v_cndmask_b32_e32 v59, v208, v59, vcc
	v_cmp_le_i32_e32 vcc, v172, v187
	s_nop 1
	v_cndmask_b32_e32 v43, v208, v43, vcc
	v_cmp_le_i32_e32 vcc, v173, v187
	s_nop 1
	v_cndmask_b32_e32 v60, v208, v60, vcc
	v_cmp_le_i32_e32 vcc, v174, v187
	s_nop 1
	v_cndmask_b32_e32 v44, v208, v44, vcc
	v_cmp_le_i32_e32 vcc, v175, v187
	s_nop 1
	v_cndmask_b32_e32 v61, v208, v61, vcc
	v_cmp_le_i32_e32 vcc, v176, v187
	s_nop 1
	v_cndmask_b32_e32 v45, v208, v45, vcc
	v_cmp_le_i32_e32 vcc, v177, v187
	s_nop 1
	v_cndmask_b32_e32 v62, v208, v62, vcc
	v_cmp_le_i32_e32 vcc, v178, v187
	s_nop 1
	v_cndmask_b32_e32 v46, v208, v46, vcc
	v_cmp_le_i32_e32 vcc, v179, v187
	s_nop 1
	v_cndmask_b32_e32 v63, v208, v63, vcc
	v_cmp_le_i32_e32 vcc, v180, v187
	s_nop 1
	v_cndmask_b32_e32 v47, v208, v47, vcc
	v_cmp_le_i32_e32 vcc, v181, v187
	s_nop 1
	v_cndmask_b32_e32 v64, v208, v64, vcc
	v_cmp_le_i32_e32 vcc, v182, v187
	s_nop 1
	v_cndmask_b32_e32 v48, v208, v48, vcc
	v_cmp_le_i32_e32 vcc, v183, v187
	s_nop 1
	v_cndmask_b32_e32 v65, v208, v65, vcc
	v_cmp_le_i32_e32 vcc, v184, v187
	s_nop 1
	v_cndmask_b32_e32 v49, v208, v49, vcc
